# rwkv2: role-2 waves pull the P/R/K/V rows of chunk pc+4 into L2 during their idle interval (role 1's prefetch then hits L2)
# speedup vs baseline: 1.0112x; 1.0112x over previous
; __device__ unsigned long long rwkv2_phase(const Params& p, unsigned char* smem) {
;     ...
;         } else {
;             const int ws = wave - 6;
;             float gng[4], gnb[4];
; #pragma unroll
;             for (int nt = 0; nt < 4; ++nt) { gng[nt] = p.in[37][hc + 16 * nt + l15]; gnb[nt] = p.in[38][hc + 16 * nt + l15]; }
;             f32x4 accS[2][4];
; #pragma unroll
;             for (int m = 0; m < 2; ++m)
; #pragma unroll
;                 for (int n = 0; n < 4; ++n) accS[m][n] = (f32x4){0.f, 0.f, 0.f, 0.f};
;             for (int pc = 0; pc <= NCH + 1; ++pc) {
.LBB0_878:
	s_and_b64 vcc, exec, s[26:27]
	s_cbranch_vccz .LBB0_946
	v_readlane_b32 s36, v251, 42
	v_mbcnt_lo_u32_b32 v235, -1, 0
	v_mbcnt_hi_u32_b32 v235, -1, v235
	v_bfe_u32 v236, v0, 6, 1
	s_lshr_b32 s37, s36, 6
	s_and_b32 s36, s36, 63
	s_lshl_b32 s40, s37, 25
	s_lshl_b32 s41, s36, 7
	s_add_i32 s40, s40, s41
	s_add_i32 s40, s40, 0xffffe000
	v_lshl_add_u32 v237, v236, 8, v235
	v_add_u32_e32 v238, 0, v237
	v_cmp_lt_u32_e32 vcc, 135, v238
	v_cndmask_b32_e64 v239, 0, 1, vcc
	v_cmp_lt_u32_e32 vcc, 271, v238
	v_addc_co_u32_e32 v239, vcc, 0, v239, vcc
	v_cmp_gt_u32_e32 vcc, 408, v238
	v_mul_u32_u24_e32 v240, 0x88, v239
	v_sub_u32_e32 v240, v238, v240
	v_lshrrev_b32_e32 v241, 3, v240
	v_and_b32_e32 v240, 7, v240
	v_lshlrev_b32_e32 v241, 13, v241
	v_lshl_add_u32 v241, v240, 4, v241
	v_lshlrev_b32_e32 v239, 27, v239
	v_add3_u32 v241, v241, v239, s40
	v_add_u32_e32 v241, 0x4000000, v241
	v_mov_b32_e32 v244, 0x4000000
	v_cndmask_b32_e32 v244, v244, v241, vcc
	v_add_u32_e32 v238, 64, v237
	v_cmp_lt_u32_e32 vcc, 135, v238
	v_cndmask_b32_e64 v239, 0, 1, vcc
	v_cmp_lt_u32_e32 vcc, 271, v238
	v_addc_co_u32_e32 v239, vcc, 0, v239, vcc
	v_cmp_gt_u32_e32 vcc, 408, v238
	v_mul_u32_u24_e32 v240, 0x88, v239
	v_sub_u32_e32 v240, v238, v240
	v_lshrrev_b32_e32 v241, 3, v240
	v_and_b32_e32 v240, 7, v240
	v_lshlrev_b32_e32 v241, 13, v241
	v_lshl_add_u32 v241, v240, 4, v241
	v_lshlrev_b32_e32 v239, 27, v239
	v_add3_u32 v241, v241, v239, s40
	v_add_u32_e32 v241, 0x4000000, v241
	v_mov_b32_e32 v245, 0x4000000
	v_cndmask_b32_e32 v245, v245, v241, vcc
	v_add_u32_e32 v238, 128, v237
	v_cmp_lt_u32_e32 vcc, 135, v238
	v_cndmask_b32_e64 v239, 0, 1, vcc
	v_cmp_lt_u32_e32 vcc, 271, v238
	v_addc_co_u32_e32 v239, vcc, 0, v239, vcc
	v_cmp_gt_u32_e32 vcc, 408, v238
	v_mul_u32_u24_e32 v240, 0x88, v239
	v_sub_u32_e32 v240, v238, v240
	v_lshrrev_b32_e32 v241, 3, v240
	v_and_b32_e32 v240, 7, v240
	v_lshlrev_b32_e32 v241, 13, v241
	v_lshl_add_u32 v241, v240, 4, v241
	v_lshlrev_b32_e32 v239, 27, v239
	v_add3_u32 v241, v241, v239, s40
	v_add_u32_e32 v241, 0x4000000, v241
	v_mov_b32_e32 v246, 0x4000000
	v_cndmask_b32_e32 v246, v246, v241, vcc
	v_add_u32_e32 v238, 192, v237
	v_cmp_lt_u32_e32 vcc, 135, v238
	v_cndmask_b32_e64 v239, 0, 1, vcc
	v_cmp_lt_u32_e32 vcc, 271, v238
	v_addc_co_u32_e32 v239, vcc, 0, v239, vcc
	v_cmp_gt_u32_e32 vcc, 408, v238
	v_mul_u32_u24_e32 v240, 0x88, v239
	v_sub_u32_e32 v240, v238, v240
	v_lshrrev_b32_e32 v241, 3, v240
	v_and_b32_e32 v240, 7, v240
	v_lshlrev_b32_e32 v241, 13, v241
	v_lshl_add_u32 v241, v240, 4, v241
	v_lshlrev_b32_e32 v239, 27, v239
	v_add3_u32 v241, v241, v239, s40
	v_add_u32_e32 v241, 0x4000000, v241
	v_mov_b32_e32 v247, 0x4000000
	v_cndmask_b32_e32 v247, v247, v241, vcc
	s_mul_i32 s40, s37, 0x300000
	s_add_i32 s40, s40, 0x1f200000
	v_mul_u32_u24_e32 v238, 0x1800, v236
	v_lshl_add_u32 v238, v235, 4, v238
	v_add_u32_e32 v248, s40, v238
	s_mov_b32 s30, 0
	s_branch .LBB0_882

; #define LBARW() do { if (PROBE_ROLE >= 0 && wave == PROBE_ROLE) { const unsigned long long tb_ = __builtin_amdgcn_s_memrealtime(); LBAR(); twait += __builtin_amdgcn_s_memrealtime() - tb_; } else { LBAR(); } } while (0)
; __device__ unsigned long long rwkv2_phase(const Params& p, unsigned char* smem) {
;     ...
;                 LBARW();
;             }
.LBB0_922:
	s_waitcnt lgkmcnt(0)
	s_barrier
	s_add_i32 s40, s30, 4
	s_cmpk_gt_u32 s40, 0xff
	s_cbranch_scc1 RWPULL_skip
	v_readlane_b32 s38, v251, 36
	v_readlane_b32 s39, v251, 37
	s_lshl_b32 s41, s40, 17
	s_mul_i32 s42, s40, 0x3000
	v_add_u32_e32 v235, s41, v244
	v_add_u32_e32 v236, s41, v245
	v_add_u32_e32 v237, s41, v246
	v_add_u32_e32 v238, s41, v247
	v_add_u32_e32 v239, s42, v248
	global_load_dwordx4 v[240:243], v235, s[38:39]
	global_load_dwordx4 v[240:243], v236, s[38:39]
	global_load_dwordx4 v[240:243], v237, s[38:39]
	global_load_dwordx4 v[240:243], v238, s[38:39]
	global_load_dwordx4 v[240:243], v239, s[38:39]
	global_load_dwordx4 v[240:243], v239, s[38:39] offset:1024
	global_load_dwordx4 v[240:243], v239, s[38:39] offset:2048
	global_load_dwordx4 v[240:243], v239, s[38:39] offset:3072
	v_add_u32_e32 v239, 0x1000, v239
	global_load_dwordx4 v[240:243], v239, s[38:39]
	global_load_dwordx4 v[240:243], v239, s[38:39] offset:1024
RWPULL_skip:
	s_cmpk_lt_i32 s30, 0x101
	s_cbranch_scc1 .LBB0_924
	s_cmpk_lg_i32 s30, 0x101
	s_cselect_b64 s[26:27], -1, 0
	s_cbranch_execz .LBB0_925
	s_branch .LBB0_926
